# v58: v57 without the pre-barrier lgkmcnt(8) in the two 12-read in-proj load sections (first consumers carry counted waits)
# speedup vs baseline: 1.0004x; 1.0001x over previous
; #define G_STAGE(bufoff, gbase, voff) do { _Pragma("unroll") for (int _i = 0; _i < 2; ++_i) \
;     __builtin_amdgcn_global_load_lds((const unsigned*)((const char*)(gbase) + (voff)[_i]), (LAS unsigned*)(lds + (bufoff) + ldsw + _i * 8192), 16, 0, 0); } while (0)
; #define G_LDA(dst, b, h) do { _Pragma("unroll") for (int m = 0; m < 4; ++m) _Pragma("unroll") for (int k = 0; k < 2; ++k) dst[m][k] = *(const LAS bf16x8*)(lds + G_SA(b, h) + aoff + m * 2048 + k * 1024); } while (0)
; #define G_LDB(dst, b, h) do { _Pragma("unroll") for (int n = 0; n < 2; ++n) _Pragma("unroll") for (int k = 0; k < 2; ++k) dst[n][k] = *(const LAS bf16x8*)(lds + G_SB(b, h) + boff + n * 2048 + k * 1024); } while (0)
; #define G_MMA(ai, bj, At, Bt) do { __builtin_amdgcn_s_setprio(1); _Pragma("unroll") for (int m = 0; m < 4; ++m) _Pragma("unroll") for (int n = 0; n < 2; ++n) _Pragma("unroll") for (int k = 0; k < 2; ++k) \
;     acc[ai][bj][m][n] = __builtin_amdgcn_mfma_f32_16x16x32_bf16(Bt[n][k], At[m][k], acc[ai][bj][m][n], 0, 0, 0); __builtin_amdgcn_s_setprio(0); } while (0)
; #define G_WAIT_V(n) asm volatile("s_waitcnt vmcnt(" #n ")" ::: "memory")
; #define G_WAIT_L(n) asm volatile("s_waitcnt lgkmcnt(" #n ")" ::: "memory")
; #define G_BAR __builtin_amdgcn_s_barrier()
; #define G_SCHED __builtin_amdgcn_sched_barrier(0)
; template <int GP> DI void gemm_phase(const Params& p, int l, int which, char* smem, int wv) {
;     ...
;       G_LDB(B0, 0, 0); G_SCHED; G_LDA(At, 0, 0); G_STAGE(G_SA(1, 1), a1 + hstep, voffA);
;       G_WAIT_L(8); G_BAR; G_WAIT_L(0); G_MMA(0, 0, At, B0); G_BAR; G_SCHED;
;       G_LDB(B1, 0, 1); G_STAGE(G_SB(0, 0), b2, vb0);
;       G_BAR; G_WAIT_L(0); G_MMA(0, 1, At, B1); G_BAR;
;       G_LDA(At, 0, 1); G_STAGE(G_SA(0, 0), a2, voffA);
;       G_BAR; G_WAIT_L(0); G_MMA(1, 0, At, B0); G_BAR; G_SCHED;
;       G_STAGE(G_SB(0, 1), b2, vb1);
;       G_WAIT_V(6); G_BAR; G_MMA(1, 1, At, B1); G_BAR;
;       G_LDB(B0, 1, 0); G_SCHED; G_LDA(At, 1, 0); G_STAGE(G_SA(0, 1), a2 + hstep, voffA);
;       G_WAIT_L(8); G_BAR; G_WAIT_L(0); G_MMA(0, 0, At, B0); G_BAR; G_SCHED;
;       G_LDB(B1, 1, 1); G_STAGE(G_SB(1, 0), b3, vb0);
;       G_BAR; G_WAIT_L(0); G_MMA(0, 1, At, B1); G_BAR;
;       G_LDA(At, 1, 1); G_STAGE(G_SA(1, 0), a3, voffA);
;       G_BAR; G_WAIT_L(0); G_MMA(1, 0, At, B0); G_BAR; G_SCHED;
;       G_STAGE(G_SB(1, 1), b3, vb1);
;       G_WAIT_V(6); G_BAR; G_MMA(1, 1, At, B1); G_BAR;
.Lkf_top:
	ds_read_b128 v[148:151], v228
	ds_read_b128 v[152:155], v228 offset:1024
	ds_read_b128 v[156:159], v228 offset:2048
	ds_read_b128 v[160:163], v228 offset:3072
	ds_read_b128 v[164:167], v211
	ds_read_b128 v[168:171], v211 offset:1024
	ds_read_b128 v[172:175], v211 offset:2048
	ds_read_b128 v[176:179], v211 offset:3072
	ds_read_b128 v[180:183], v211 offset:4096
	ds_read_b128 v[184:187], v211 offset:5120
	ds_read_b128 v[188:191], v211 offset:6144
	ds_read_b128 v[192:195], v211 offset:7168
	global_load_lds_dwordx4 v138, s[100:101]
	s_add_i32 m0, s23, 0xe000
	s_nop 0
	global_load_lds_dwordx4 v140, s[100:101]
	s_barrier
	s_waitcnt lgkmcnt(7)
	v_mfma_f32_16x16x32_bf16 v[62:65], v[148:151], v[164:167], v[62:65]
	v_mfma_f32_16x16x32_bf16 v[58:61], v[156:159], v[164:167], v[58:61]
	s_mov_b32 m0, s25
	s_waitcnt lgkmcnt(5)
	v_mfma_f32_16x16x32_bf16 v[54:57], v[148:151], v[172:175], v[54:57]
	v_mfma_f32_16x16x32_bf16 v[50:53], v[156:159], v[172:175], v[50:53]
	s_waitcnt lgkmcnt(3)
	v_mfma_f32_16x16x32_bf16 v[46:49], v[148:151], v[180:183], v[46:49]
	v_mfma_f32_16x16x32_bf16 v[42:45], v[156:159], v[180:183], v[42:45]
	s_waitcnt lgkmcnt(1)
	v_mfma_f32_16x16x32_bf16 v[38:41], v[148:151], v[188:191], v[38:41]
	v_mfma_f32_16x16x32_bf16 v[34:37], v[156:159], v[188:191], v[34:37]
	v_mfma_f32_16x16x32_bf16 v[62:65], v[152:155], v[168:171], v[62:65]
	v_mfma_f32_16x16x32_bf16 v[58:61], v[160:163], v[168:171], v[58:61]
	v_mfma_f32_16x16x32_bf16 v[54:57], v[152:155], v[176:179], v[54:57]
	v_mfma_f32_16x16x32_bf16 v[50:53], v[160:163], v[176:179], v[50:53]
	v_mfma_f32_16x16x32_bf16 v[46:49], v[152:155], v[184:187], v[46:49]
	v_mfma_f32_16x16x32_bf16 v[42:45], v[160:163], v[184:187], v[42:45]
	s_waitcnt lgkmcnt(0)
	v_mfma_f32_16x16x32_bf16 v[38:41], v[152:155], v[192:195], v[38:41]
	v_mfma_f32_16x16x32_bf16 v[34:37], v[160:163], v[192:195], v[34:37]
	s_barrier
	ds_read_b128 v[196:199], v228 offset:16384
	ds_read_b128 v[200:203], v228 offset:17408
	ds_read_b128 v[204:207], v228 offset:18432
	ds_read_b128 v[238:241], v228 offset:19456
	global_load_lds_dwordx4 v0, s[6:7]
	s_mov_b32 m0, s58
	s_nop 0
	global_load_lds_dwordx4 v136, s[6:7]
	s_barrier
	s_waitcnt lgkmcnt(0)
	v_mfma_f32_16x16x32_bf16 v[30:33], v[196:199], v[164:167], v[30:33]
	v_mfma_f32_16x16x32_bf16 v[26:29], v[204:207], v[164:167], v[26:29]
	s_mov_b32 m0, s23
	v_mfma_f32_16x16x32_bf16 v[22:25], v[196:199], v[172:175], v[22:25]
	v_mfma_f32_16x16x32_bf16 v[18:21], v[204:207], v[172:175], v[18:21]
	v_mfma_f32_16x16x32_bf16 v[14:17], v[196:199], v[180:183], v[14:17]
	v_mfma_f32_16x16x32_bf16 v[10:13], v[204:207], v[180:183], v[10:13]
	v_mfma_f32_16x16x32_bf16 v[6:9], v[196:199], v[188:191], v[6:9]
	v_mfma_f32_16x16x32_bf16 v[2:5], v[204:207], v[188:191], v[2:5]
	v_mfma_f32_16x16x32_bf16 v[30:33], v[200:203], v[168:171], v[30:33]
	v_mfma_f32_16x16x32_bf16 v[26:29], v[238:241], v[168:171], v[26:29]
	v_mfma_f32_16x16x32_bf16 v[22:25], v[200:203], v[176:179], v[22:25]
	v_mfma_f32_16x16x32_bf16 v[18:21], v[238:241], v[176:179], v[18:21]
	v_mfma_f32_16x16x32_bf16 v[14:17], v[200:203], v[184:187], v[14:17]
	v_mfma_f32_16x16x32_bf16 v[10:13], v[238:241], v[184:187], v[10:13]
	v_mfma_f32_16x16x32_bf16 v[6:9], v[200:203], v[192:195], v[6:9]
	v_mfma_f32_16x16x32_bf16 v[2:5], v[238:241], v[192:195], v[2:5]
	s_barrier
	ds_read_b128 v[164:167], v211 offset:16384
	ds_read_b128 v[168:171], v211 offset:17408
	ds_read_b128 v[172:175], v211 offset:18432
	ds_read_b128 v[176:179], v211 offset:19456
	ds_read_b128 v[180:183], v211 offset:20480
	ds_read_b128 v[184:187], v211 offset:21504
	ds_read_b128 v[188:191], v211 offset:22528
	ds_read_b128 v[192:195], v211 offset:23552
	global_load_lds_dwordx4 v132, s[8:9]
	s_mov_b32 m0, s59
	s_nop 0
	global_load_lds_dwordx4 v134, s[8:9]
	s_barrier
	s_waitcnt lgkmcnt(0)
	v_mfma_f32_16x16x32_bf16 v[66:69], v[148:151], v[164:167], v[66:69]
	v_mfma_f32_16x16x32_bf16 v[70:73], v[156:159], v[164:167], v[70:73]
	s_mov_b32 m0, s60
	v_mfma_f32_16x16x32_bf16 v[74:77], v[148:151], v[172:175], v[74:77]
	v_mfma_f32_16x16x32_bf16 v[78:81], v[156:159], v[172:175], v[78:81]
	v_mfma_f32_16x16x32_bf16 v[82:85], v[148:151], v[180:183], v[82:85]
	v_mfma_f32_16x16x32_bf16 v[86:89], v[156:159], v[180:183], v[86:89]
	v_mfma_f32_16x16x32_bf16 v[90:93], v[148:151], v[188:191], v[90:93]
	v_mfma_f32_16x16x32_bf16 v[94:97], v[156:159], v[188:191], v[94:97]
	v_mfma_f32_16x16x32_bf16 v[66:69], v[152:155], v[168:171], v[66:69]
	v_mfma_f32_16x16x32_bf16 v[70:73], v[160:163], v[168:171], v[70:73]
	v_mfma_f32_16x16x32_bf16 v[74:77], v[152:155], v[176:179], v[74:77]
	v_mfma_f32_16x16x32_bf16 v[78:81], v[160:163], v[176:179], v[78:81]
	v_mfma_f32_16x16x32_bf16 v[82:85], v[152:155], v[184:187], v[82:85]
	v_mfma_f32_16x16x32_bf16 v[86:89], v[160:163], v[184:187], v[86:89]
	v_mfma_f32_16x16x32_bf16 v[90:93], v[152:155], v[192:195], v[90:93]
	v_mfma_f32_16x16x32_bf16 v[94:97], v[160:163], v[192:195], v[94:97]
	s_barrier
	global_load_lds_dwordx4 v130, s[6:7]
	s_mov_b32 m0, s61
	s_nop 0
	global_load_lds_dwordx4 v142, s[6:7]
	s_waitcnt vmcnt(6)
	s_barrier
; #define G_STAGE(bufoff, gbase, voff) do { _Pragma("unroll") for (int _i = 0; _i < 2; ++_i) \
;     __builtin_amdgcn_global_load_lds((const unsigned*)((const char*)(gbase) + (voff)[_i]), (LAS unsigned*)(lds + (bufoff) + ldsw + _i * 8192), 16, 0, 0); } while (0)
; #define G_LDA(dst, b, h) do { _Pragma("unroll") for (int m = 0; m < 4; ++m) _Pragma("unroll") for (int k = 0; k < 2; ++k) dst[m][k] = *(const LAS bf16x8*)(lds + G_SA(b, h) + aoff + m * 2048 + k * 1024); } while (0)
; #define G_LDB(dst, b, h) do { _Pragma("unroll") for (int n = 0; n < 2; ++n) _Pragma("unroll") for (int k = 0; k < 2; ++k) dst[n][k] = *(const LAS bf16x8*)(lds + G_SB(b, h) + boff + n * 2048 + k * 1024); } while (0)
; #define G_MMA(ai, bj, At, Bt) do { __builtin_amdgcn_s_setprio(1); _Pragma("unroll") for (int m = 0; m < 4; ++m) _Pragma("unroll") for (int n = 0; n < 2; ++n) _Pragma("unroll") for (int k = 0; k < 2; ++k) \
;     acc[ai][bj][m][n] = __builtin_amdgcn_mfma_f32_16x16x32_bf16(Bt[n][k], At[m][k], acc[ai][bj][m][n], 0, 0, 0); __builtin_amdgcn_s_setprio(0); } while (0)
; #define G_WAIT_V(n) asm volatile("s_waitcnt vmcnt(" #n ")" ::: "memory")
; #define G_WAIT_L(n) asm volatile("s_waitcnt lgkmcnt(" #n ")" ::: "memory")
; #define G_BAR __builtin_amdgcn_s_barrier()
; #define G_SCHED __builtin_amdgcn_sched_barrier(0)
; template <int GP> DI void gemm_phase(const Params& p, int l, int which, char* smem, int wv) {
;     ...
;       G_LDB(B0, 0, 0); G_SCHED; G_LDA(At, 0, 0); G_STAGE(G_SA(1, 1), a1 + hstep, voffA);
;       G_WAIT_L(8); G_BAR; G_WAIT_L(0); G_MMA(0, 0, At, B0); G_BAR; G_SCHED;
;       G_LDB(B1, 0, 1); G_STAGE(G_SB(0, 0), b2, vb0);
;       G_BAR; G_WAIT_L(0); G_MMA(0, 1, At, B1); G_BAR;
;       G_LDA(At, 0, 1); G_STAGE(G_SA(0, 0), a2, voffA);
;       G_BAR; G_WAIT_L(0); G_MMA(1, 0, At, B0); G_BAR; G_SCHED;
;       G_STAGE(G_SB(0, 1), b2, vb1);
;       G_WAIT_V(6); G_BAR; G_MMA(1, 1, At, B1); G_BAR;
;       G_LDB(B0, 1, 0); G_SCHED; G_LDA(At, 1, 0); G_STAGE(G_SA(0, 1), a2 + hstep, voffA);
;       G_WAIT_L(8); G_BAR; G_WAIT_L(0); G_MMA(0, 0, At, B0); G_BAR; G_SCHED;
;       G_LDB(B1, 1, 1); G_STAGE(G_SB(1, 0), b3, vb0);
;       G_BAR; G_WAIT_L(0); G_MMA(0, 1, At, B1); G_BAR;
;       G_LDA(At, 1, 1); G_STAGE(G_SA(1, 0), a3, voffA);
;       G_BAR; G_WAIT_L(0); G_MMA(1, 0, At, B0); G_BAR; G_SCHED;
;       G_STAGE(G_SB(1, 1), b3, vb1);
;       G_WAIT_V(6); G_BAR; G_MMA(1, 1, At, B1); G_BAR;
	v_mfma_f32_16x16x32_bf16 v[98:101], v[196:199], v[164:167], v[98:101]
	v_mfma_f32_16x16x32_bf16 v[102:105], v[204:207], v[164:167], v[102:105]
	s_add_u32 s100, s8, 0x80000
	s_addc_u32 s101, s9, 0
	s_mov_b32 m0, s62
	v_mfma_f32_16x16x32_bf16 v[106:109], v[196:199], v[172:175], v[106:109]
	v_mfma_f32_16x16x32_bf16 v[110:113], v[204:207], v[172:175], v[110:113]
	v_mfma_f32_16x16x32_bf16 v[114:117], v[196:199], v[180:183], v[114:117]
	v_mfma_f32_16x16x32_bf16 v[118:121], v[204:207], v[180:183], v[118:121]
	v_mfma_f32_16x16x32_bf16 v[122:125], v[196:199], v[188:191], v[122:125]
	v_mfma_f32_16x16x32_bf16 v[126:129], v[204:207], v[188:191], v[126:129]
	v_mfma_f32_16x16x32_bf16 v[98:101], v[200:203], v[168:171], v[98:101]
	v_mfma_f32_16x16x32_bf16 v[102:105], v[238:241], v[168:171], v[102:105]
	v_mfma_f32_16x16x32_bf16 v[106:109], v[200:203], v[176:179], v[106:109]
	v_mfma_f32_16x16x32_bf16 v[110:113], v[238:241], v[176:179], v[110:113]
	v_mfma_f32_16x16x32_bf16 v[114:117], v[200:203], v[184:187], v[114:117]
	v_mfma_f32_16x16x32_bf16 v[118:121], v[238:241], v[184:187], v[118:121]
	v_mfma_f32_16x16x32_bf16 v[122:125], v[200:203], v[192:195], v[122:125]
	v_mfma_f32_16x16x32_bf16 v[126:129], v[238:241], v[192:195], v[126:129]
	s_barrier
	ds_read_b128 v[148:151], v228 offset:32768
	ds_read_b128 v[152:155], v228 offset:33792
	ds_read_b128 v[156:159], v228 offset:34816
	ds_read_b128 v[160:163], v228 offset:35840
	ds_read_b128 v[164:167], v211 offset:32768
	ds_read_b128 v[168:171], v211 offset:33792
	ds_read_b128 v[172:175], v211 offset:34816
	ds_read_b128 v[176:179], v211 offset:35840
	ds_read_b128 v[180:183], v211 offset:36864
	ds_read_b128 v[184:187], v211 offset:37888
	ds_read_b128 v[188:191], v211 offset:38912
	ds_read_b128 v[192:195], v211 offset:39936
	global_load_lds_dwordx4 v132, s[100:101]
	s_mov_b32 m0, s63
	s_nop 0
	global_load_lds_dwordx4 v134, s[100:101]
	s_barrier
	s_waitcnt lgkmcnt(7)
	v_mfma_f32_16x16x32_bf16 v[62:65], v[148:151], v[164:167], v[62:65]
	v_mfma_f32_16x16x32_bf16 v[58:61], v[156:159], v[164:167], v[58:61]
	s_mov_b32 m0, s21
	s_add_u32 s100, s6, s16
	s_addc_u32 s101, s7, s17
	s_waitcnt lgkmcnt(5)
	v_mfma_f32_16x16x32_bf16 v[54:57], v[148:151], v[172:175], v[54:57]
	v_mfma_f32_16x16x32_bf16 v[50:53], v[156:159], v[172:175], v[50:53]
	s_waitcnt lgkmcnt(3)
	v_mfma_f32_16x16x32_bf16 v[46:49], v[148:151], v[180:183], v[46:49]
	v_mfma_f32_16x16x32_bf16 v[42:45], v[156:159], v[180:183], v[42:45]
	s_waitcnt lgkmcnt(1)
	v_mfma_f32_16x16x32_bf16 v[38:41], v[148:151], v[188:191], v[38:41]
	v_mfma_f32_16x16x32_bf16 v[34:37], v[156:159], v[188:191], v[34:37]
	v_mfma_f32_16x16x32_bf16 v[62:65], v[152:155], v[168:171], v[62:65]
	v_mfma_f32_16x16x32_bf16 v[58:61], v[160:163], v[168:171], v[58:61]
	v_mfma_f32_16x16x32_bf16 v[54:57], v[152:155], v[176:179], v[54:57]
	v_mfma_f32_16x16x32_bf16 v[50:53], v[160:163], v[176:179], v[50:53]
	v_mfma_f32_16x16x32_bf16 v[46:49], v[152:155], v[184:187], v[46:49]
	v_mfma_f32_16x16x32_bf16 v[42:45], v[160:163], v[184:187], v[42:45]
	s_waitcnt lgkmcnt(0)
	v_mfma_f32_16x16x32_bf16 v[38:41], v[152:155], v[192:195], v[38:41]
	v_mfma_f32_16x16x32_bf16 v[34:37], v[160:163], v[192:195], v[34:37]
	s_barrier
	ds_read_b128 v[196:199], v228 offset:49152
	ds_read_b128 v[200:203], v228 offset:50176
	ds_read_b128 v[204:207], v228 offset:51200
	ds_read_b128 v[238:241], v228 offset:52224
	global_load_lds_dwordx4 v0, s[100:101]
	s_mov_b32 m0, s64
	s_nop 0
	global_load_lds_dwordx4 v136, s[100:101]
	s_barrier
; #define G_STAGE(bufoff, gbase, voff) do { _Pragma("unroll") for (int _i = 0; _i < 2; ++_i) \
;     __builtin_amdgcn_global_load_lds((const unsigned*)((const char*)(gbase) + (voff)[_i]), (LAS unsigned*)(lds + (bufoff) + ldsw + _i * 8192), 16, 0, 0); } while (0)
; #define G_LDA(dst, b, h) do { _Pragma("unroll") for (int m = 0; m < 4; ++m) _Pragma("unroll") for (int k = 0; k < 2; ++k) dst[m][k] = *(const LAS bf16x8*)(lds + G_SA(b, h) + aoff + m * 2048 + k * 1024); } while (0)
; #define G_LDB(dst, b, h) do { _Pragma("unroll") for (int n = 0; n < 2; ++n) _Pragma("unroll") for (int k = 0; k < 2; ++k) dst[n][k] = *(const LAS bf16x8*)(lds + G_SB(b, h) + boff + n * 2048 + k * 1024); } while (0)
; #define G_WAIT_V(n) asm volatile("s_waitcnt vmcnt(" #n ")" ::: "memory")
; #define G_BAR __builtin_amdgcn_s_barrier()
; template <int GP> DI void gemm_phase(const Params& p, int l, int which, char* smem, int wv) {
;     ...
;     for (int t = 0; t < cnk; t += 2) {
;       const bool last = (t == cnk - 2);
;       const char* a1 = cA + (size_t)(t + 1) * kstep;
;       const char* a2 = last ? nA : cA + (size_t)(t + 2) * kstep; const char* b2 = last ? nB : cB + (size_t)(t + 2) * kstep;
;       const char* a3 = a2 + kstep; const char* b3 = b2 + kstep;
;       if (last) {
; #pragma unroll
;         for (int i = 0; i < 2; ++i) { vb0[i] = voffB(i, 0, n32); vb1[i] = voffB(i, 1, n32); }
;       }
;       G_LDB(B0, 0, 0); G_SCHED; G_LDA(At, 0, 0); G_STAGE(G_SA(1, 1), a1 + hstep, voffA);
;       G_WAIT_L(8); G_BAR; G_WAIT_L(0); G_MMA(0, 0, At, B0); G_BAR; G_SCHED;
;       G_LDB(B1, 0, 1); G_STAGE(G_SB(0, 0), b2, vb0);
;       G_BAR; G_WAIT_L(0); G_MMA(0, 1, At, B1); G_BAR;
;       G_LDA(At, 0, 1); G_STAGE(G_SA(0, 0), a2, voffA);
;       G_BAR; G_WAIT_L(0); G_MMA(1, 0, At, B0); G_BAR; G_SCHED;
;       G_STAGE(G_SB(0, 1), b2, vb1);
;       G_WAIT_V(6); G_BAR; G_MMA(1, 1, At, B1); G_BAR;
;       G_LDB(B0, 1, 0); G_SCHED; G_LDA(At, 1, 0); G_STAGE(G_SA(0, 1), a2 + hstep, voffA);
;       G_WAIT_L(8); G_BAR; G_WAIT_L(0); G_MMA(0, 0, At, B0); G_BAR; G_SCHED;
;       G_LDB(B1, 1, 1); G_STAGE(G_SB(1, 0), b3, vb0);
;       G_BAR; G_WAIT_L(0); G_MMA(0, 1, At, B1); G_BAR;
;       G_LDA(At, 1, 1); G_STAGE(G_SA(1, 0), a3, voffA);
;       G_BAR; G_WAIT_L(0); G_MMA(1, 0, At, B0); G_BAR; G_SCHED;
;       G_STAGE(G_SB(1, 1), b3, vb1);
;       G_WAIT_V(6); G_BAR; G_MMA(1, 1, At, B1); G_BAR;
	s_waitcnt lgkmcnt(0)
	v_mfma_f32_16x16x32_bf16 v[30:33], v[196:199], v[164:167], v[30:33]
	v_mfma_f32_16x16x32_bf16 v[26:29], v[204:207], v[164:167], v[26:29]
	s_mov_b32 m0, s65
	s_add_u32 s100, s8, s16
	s_addc_u32 s101, s9, s17
	v_mfma_f32_16x16x32_bf16 v[22:25], v[196:199], v[172:175], v[22:25]
	v_mfma_f32_16x16x32_bf16 v[18:21], v[204:207], v[172:175], v[18:21]
	v_mfma_f32_16x16x32_bf16 v[14:17], v[196:199], v[180:183], v[14:17]
	v_mfma_f32_16x16x32_bf16 v[10:13], v[204:207], v[180:183], v[10:13]
	v_mfma_f32_16x16x32_bf16 v[6:9], v[196:199], v[188:191], v[6:9]
	v_mfma_f32_16x16x32_bf16 v[2:5], v[204:207], v[188:191], v[2:5]
	v_mfma_f32_16x16x32_bf16 v[30:33], v[200:203], v[168:171], v[30:33]
	v_mfma_f32_16x16x32_bf16 v[26:29], v[238:241], v[168:171], v[26:29]
	v_mfma_f32_16x16x32_bf16 v[22:25], v[200:203], v[176:179], v[22:25]
	v_mfma_f32_16x16x32_bf16 v[18:21], v[238:241], v[176:179], v[18:21]
	v_mfma_f32_16x16x32_bf16 v[14:17], v[200:203], v[184:187], v[14:17]
	v_mfma_f32_16x16x32_bf16 v[10:13], v[238:241], v[184:187], v[10:13]
	v_mfma_f32_16x16x32_bf16 v[6:9], v[200:203], v[192:195], v[6:9]
	v_mfma_f32_16x16x32_bf16 v[2:5], v[238:241], v[192:195], v[2:5]
	s_barrier
	ds_read_b128 v[164:167], v211 offset:49152
	ds_read_b128 v[168:171], v211 offset:50176
	ds_read_b128 v[172:175], v211 offset:51200
	ds_read_b128 v[176:179], v211 offset:52224
	ds_read_b128 v[180:183], v211 offset:53248
	ds_read_b128 v[184:187], v211 offset:54272
	ds_read_b128 v[188:191], v211 offset:55296
	ds_read_b128 v[192:195], v211 offset:56320
	global_load_lds_dwordx4 v132, s[100:101]
	s_mov_b32 m0, s66
	s_nop 0
	global_load_lds_dwordx4 v134, s[100:101]
	s_barrier
	s_waitcnt lgkmcnt(0)
	v_mfma_f32_16x16x32_bf16 v[66:69], v[148:151], v[164:167], v[66:69]
	v_mfma_f32_16x16x32_bf16 v[70:73], v[156:159], v[164:167], v[70:73]
	s_mov_b32 m0, s67
	s_add_u32 s100, s6, s16
	s_addc_u32 s101, s7, s17
	v_mfma_f32_16x16x32_bf16 v[74:77], v[148:151], v[172:175], v[74:77]
	v_mfma_f32_16x16x32_bf16 v[78:81], v[156:159], v[172:175], v[78:81]
	v_mfma_f32_16x16x32_bf16 v[82:85], v[148:151], v[180:183], v[82:85]
	v_mfma_f32_16x16x32_bf16 v[86:89], v[156:159], v[180:183], v[86:89]
	v_mfma_f32_16x16x32_bf16 v[90:93], v[148:151], v[188:191], v[90:93]
	v_mfma_f32_16x16x32_bf16 v[94:97], v[156:159], v[188:191], v[94:97]
	v_mfma_f32_16x16x32_bf16 v[66:69], v[152:155], v[168:171], v[66:69]
	v_mfma_f32_16x16x32_bf16 v[70:73], v[160:163], v[168:171], v[70:73]
	v_mfma_f32_16x16x32_bf16 v[74:77], v[152:155], v[176:179], v[74:77]
	v_mfma_f32_16x16x32_bf16 v[78:81], v[160:163], v[176:179], v[78:81]
	v_mfma_f32_16x16x32_bf16 v[82:85], v[152:155], v[184:187], v[82:85]
	v_mfma_f32_16x16x32_bf16 v[86:89], v[160:163], v[184:187], v[86:89]
	v_mfma_f32_16x16x32_bf16 v[90:93], v[152:155], v[192:195], v[90:93]
	v_mfma_f32_16x16x32_bf16 v[94:97], v[160:163], v[192:195], v[94:97]
	s_barrier
	global_load_lds_dwordx4 v130, s[100:101]
	s_mov_b32 m0, s68
	s_nop 0
	global_load_lds_dwordx4 v142, s[100:101]
	s_waitcnt vmcnt(6)
	s_barrier
	v_mfma_f32_16x16x32_bf16 v[98:101], v[196:199], v[164:167], v[98:101]
	v_mfma_f32_16x16x32_bf16 v[102:105], v[204:207], v[164:167], v[102:105]
	s_add_i32 m0, s23, 0xc000
	v_mfma_f32_16x16x32_bf16 v[106:109], v[196:199], v[172:175], v[106:109]
	v_mfma_f32_16x16x32_bf16 v[110:113], v[204:207], v[172:175], v[110:113]
	v_mfma_f32_16x16x32_bf16 v[114:117], v[196:199], v[180:183], v[114:117]
	v_mfma_f32_16x16x32_bf16 v[118:121], v[204:207], v[180:183], v[118:121]
	v_mfma_f32_16x16x32_bf16 v[122:125], v[196:199], v[188:191], v[122:125]
	v_mfma_f32_16x16x32_bf16 v[126:129], v[204:207], v[188:191], v[126:129]
	v_mfma_f32_16x16x32_bf16 v[98:101], v[200:203], v[168:171], v[98:101]
	s_add_i32 s50, s50, 2
	s_add_u32 s2, s2, 0x100
	s_addc_u32 s3, s3, 0
	v_mfma_f32_16x16x32_bf16 v[102:105], v[238:241], v[168:171], v[102:105]
	s_add_u32 s8, s28, s2
	s_addc_u32 s9, s29, s3
	v_mfma_f32_16x16x32_bf16 v[106:109], v[200:203], v[176:179], v[106:109]
	s_add_u32 s100, s8, 0x80080
	s_addc_u32 s101, s9, 0
	v_mfma_f32_16x16x32_bf16 v[110:113], v[238:241], v[176:179], v[110:113]
	s_add_u32 s8, s8, 0x100
	s_addc_u32 s9, s9, 0
	v_mfma_f32_16x16x32_bf16 v[114:117], v[200:203], v[184:187], v[114:117]
	s_add_u32 s6, s74, s2
	s_addc_u32 s7, s75, s3
	s_branch .Lkf_rot
